# v51 + no-tail workgroups delayed ~8 us in merge and ~4 us in out phase (run 1)
# speedup vs baseline: 1.0078x; 1.0031x over previous
; #define GAS __attribute__((address_space(1)))
;     __device__ __forceinline__ GAS unsigned char* wsp() const { return (GAS unsigned char*)rd(18); }
; __global__ void __launch_bounds__(512, 2) mega_fwd(Params p) {
;     ...
;         if (IN(pb + 3)) { pg8::Gemm g{(const GAS bf16*)(F.wsp() + WS_Y), (const GAS bf16*)(F.wsp() + WS_WBR) + (size_t)l * 3 * D * D, (size_t)MTOT * 1024, (size_t)D * D, MTOT / 256, D / 256, 3, D, MERGE_TAIL, WGM_SQ};
;             pg8::Order S; S.init(g, F.G, (int)blockIdx.x);
;             pg8::EpiMerge E{F.wsp()};
;             pg8::gemm_phase(F.lds, g, S, E, F.wave);
;             { __syncthreads(); pg8::EpiMergeSlab E2{F.wsp()}; pg8::gemm_phase<pg8::EpiMergeSlab, 1>(F.lds, g, S, E2, F.wave); }
.LBB0_931:
	s_andn2_b64 vcc, exec, s[8:9]
	s_cbranch_vccnz .LBB0_1117
	s_cmp_lg_u32 s100, 0
	s_cbranch_scc1 .Lmd_no
	s_cmpk_lt_u32 s101, 0xd8
	s_cbranch_scc1 .Lmd_no
	s_movk_i32 s99, 2
.Lmd_l:
	s_sleep 127
	s_sub_u32 s99, s99, 1
	s_cmp_lg_u32 s99, 0
	s_cbranch_scc1 .Lmd_l
.Lmd_no:
.Lmr_pre:
	v_mov_b32_e32 v0, s18
	ds_read_b64 v[0:1], v0
	v_readlane_b32 s12, v242, 56
	v_readlane_b32 s13, v242, 57
	s_andn2_b64 vcc, exec, s[12:13]
	s_waitcnt lgkmcnt(0)
	v_readfirstlane_b32 s9, v1
	v_cndmask_b32_e64 v1, 0, 1, s[12:13]
	v_readfirstlane_b32 s8, v0
	v_mov_b32_e32 v0, v173
	v_cmp_ne_u32_e64 s[56:57], 1, v1
	s_cbranch_vccnz .LBB0_934
	v_readlane_b32 s12, v242, 62
	s_mov_b32 s52, s12
	v_readlane_b32 s12, v242, 63
	s_mov_b32 s60, s12

; #define GAS __attribute__((address_space(1)))
;     __device__ __forceinline__ GAS float* outp() const { return (GAS float*)rd(17); }
;     __device__ __forceinline__ GAS unsigned char* wsp() const { return (GAS unsigned char*)rd(18); }
; __global__ void __launch_bounds__(512, 2) mega_fwd(Params p) {
;     ...
;             pg8::Gemm g{(const GAS bf16*)(F.wsp() + WS_MERGED), (const GAS bf16*)(F.wsp() + WS_WOUT) + (size_t)l * D * D, 0, 0, MTOT / 256, D / 256, 1, D, 4, WGM_SQ};
;             pg8::Order S; S.init(g, F.G, (int)blockIdx.x);
;             pg8::EpiOut E{F.wsp(), F.outp(), l == DEPTH - 1 ? 1 : 0};
;             pg8::gemm_phase(F.lds, g, S, E, F.wave);
;             { __syncthreads(); pg8::EpiOutSlab E2{F.wsp()}; pg8::gemm_phase<pg8::EpiOutSlab, 1>(F.lds, g, S, E2, F.wave); }
.LBB0_1171:
	v_readlane_b32 s8, v241, 46
	s_waitcnt lgkmcnt(0)
	s_barrier
	s_cmpk_lt_u32 s101, 0x90
	s_cbranch_scc1 .Lod_no
	s_movk_i32 s99, 1

; #define GAS __attribute__((address_space(1)))
; #define LAS __attribute__((address_space(3)))
;     __device__ __forceinline__ GAS float* outp() const { return (GAS float*)rd(17); }
;     __device__ __forceinline__ GAS unsigned char* wsp() const { return (GAS unsigned char*)rd(18); }
;     __device__ __forceinline__ unsigned long long rd(int i) const { const v2u v = *(const LAS v2u*)(lds + LDS_PARAM + 8 * i);
;         return ((unsigned long long)(unsigned)__builtin_amdgcn_readfirstlane((int)v.y) << 32) | (unsigned)__builtin_amdgcn_readfirstlane((int)v.x); }
; __global__ void __launch_bounds__(512, 2) mega_fwd(Params p) {
;     ...
;             pg8::Gemm g{(const GAS bf16*)(F.wsp() + WS_MERGED), (const GAS bf16*)(F.wsp() + WS_WOUT) + (size_t)l * D * D, 0, 0, MTOT / 256, D / 256, 1, D, 4, WGM_SQ};
;             pg8::Order S; S.init(g, F.G, (int)blockIdx.x);
;             pg8::EpiOut E{F.wsp(), F.outp(), l == DEPTH - 1 ? 1 : 0};
;             pg8::gemm_phase(F.lds, g, S, E, F.wave);
;             { __syncthreads(); pg8::EpiOutSlab E2{F.wsp()}; pg8::gemm_phase<pg8::EpiOutSlab, 1>(F.lds, g, S, E2, F.wave); }
.Lod_no:
	v_mov_b32_e32 v0, s8
	ds_read2_b64 v[0:3], v0 offset1:1
	v_readlane_b32 s14, v242, 58
	v_readlane_b32 s15, v242, 59
	s_andn2_b64 vcc, exec, s[14:15]
	s_waitcnt lgkmcnt(0)
	v_readfirstlane_b32 s9, v1
	v_cndmask_b32_e64 v1, 0, 1, s[14:15]
	v_readfirstlane_b32 s13, v3
	v_readfirstlane_b32 s12, v2
	v_readfirstlane_b32 s8, v0
	v_mov_b32_e32 v0, v173
	v_cmp_ne_u32_e64 s[58:59], 1, v1
	s_cbranch_vccnz .LBB0_1173
	v_readlane_b32 s14, v242, 62
	s_mov_b32 s60, s14
	v_readlane_b32 s14, v242, 63
	s_mov_b32 s52, s14
